# hgrn_c: state fragments staged per wave pair with 4 coalesced LDS-DMA loads per wave (XOR-swizzled source) + ds_read_b128 instead of 8 row-per-lane global loads
# speedup vs baseline: 1.0104x; 1.0027x over previous
; __device__ __forceinline__ void hgrn_c_load(Ctx& X, int u, RawC& R) {
;     const int hd = u & 7, c = u >> 3, t0 = c * 64, seg = X.tid >> 7, k = X.tid & 127;
;     const bf16_t* PR = (const bf16_t*)(X.ws + WS_PROJ);
;     const bf16_t* HQ = PR + 3 * TSZ; const bf16_t* HLF = PR + 4 * TSZ; const bf16_t* HV = PR + 5 * TSZ;
; #pragma unroll
;     for (int i = 0; i < 16; ++i) { const size_t off = (size_t)(t0 + 16 * seg + i) * 1024 + hd * 128 + k; R.lf[i] = HLF[off]; R.q[i] = HQ[off]; R.vv[i] = HV[off]; }
; }
; __global__ void __launch_bounds__(512, 2) fwd_mega(Args a) {
;     ...
;         RawC cur; hgrn_c_load(X, blockIdx.x, cur);
.LBB0_727:
	s_cmp_lt_i32 s92, 6
	s_cselect_b64 s[2:3], -1, 0
	s_and_b64 s[12:13], s[2:3], s[0:1]
	s_andn2_b64 vcc, exec, s[12:13]
	s_cbranch_vccnz .LBB0_739
	v_readlane_b32 s0, v245, 0
	s_cmpk_gt_i32 s0, 0x7ff
	v_readlane_b32 s1, v245, 1
	s_cbranch_scc1 .LBB0_739
	s_add_u32 s14, s90, 0x11700000
	s_addc_u32 s15, s91, 0
	s_add_u32 s16, s90, 0x13700000
	s_addc_u32 s17, s91, 0
	s_add_u32 s18, s90, 0x15700000
	v_lshrrev_b32_e32 v70, 3, v209
	s_addc_u32 s19, s91, 0
	v_and_b32_e32 v71, 0x70, v70
	s_and_b32 s0, s54, 0xffffffc0
	v_readlane_b32 s34, v245, 0
	v_add_u32_e32 v0, s0, v71
	s_lshl_b32 s36, s34, 7
	v_and_b32_e32 v59, 0x7f, v209
	v_or_b32_e32 v2, 8, v0
	s_and_b32 s0, s36, 0x380
	v_or_b32_e32 v22, 13, v0
	v_or_b32_e32 v26, 14, v0
	v_ashrrev_i32_e32 v3, 31, v2
	v_or_b32_e32 v1, s0, v59
	v_or_b32_e32 v6, 9, v0
	v_or_b32_e32 v10, 10, v0
	v_or_b32_e32 v12, 11, v0
	v_or_b32_e32 v14, 12, v0
	v_ashrrev_i32_e32 v23, 31, v22
	v_ashrrev_i32_e32 v27, 31, v26
	v_or_b32_e32 v30, 15, v0
	v_lshlrev_b64 v[2:3], 11, v[2:3]
	v_lshlrev_b32_e32 v38, 1, v1
	v_ashrrev_i32_e32 v7, 31, v6
	v_ashrrev_i32_e32 v11, 31, v10
	v_ashrrev_i32_e32 v13, 31, v12
	v_ashrrev_i32_e32 v15, 31, v14
	v_lshlrev_b64 v[22:23], 11, v[22:23]
	v_lshlrev_b64 v[26:27], 11, v[26:27]
	v_ashrrev_i32_e32 v31, 31, v30
	v_or_b32_e32 v2, v2, v38
	v_lshlrev_b64 v[6:7], 11, v[6:7]
	v_lshlrev_b64 v[16:17], 11, v[10:11]
	v_lshlrev_b64 v[18:19], 11, v[12:13]
	v_lshlrev_b64 v[14:15], 11, v[14:15]
	v_or_b32_e32 v22, v22, v38
	v_or_b32_e32 v26, v26, v38
	v_lshlrev_b64 v[30:31], 11, v[30:31]
	v_lshl_add_u64 v[4:5], s[18:19], 0, v[2:3]
	v_or_b32_e32 v6, v6, v38
	v_or_b32_e32 v16, v16, v38
	v_or_b32_e32 v18, v18, v38
	v_or_b32_e32 v14, v14, v38
	v_lshl_add_u64 v[24:25], s[18:19], 0, v[22:23]
	v_lshl_add_u64 v[28:29], s[18:19], 0, v[26:27]
	v_or_b32_e32 v30, v30, v38
	v_lshl_add_u64 v[8:9], s[18:19], 0, v[6:7]
	v_lshl_add_u64 v[10:11], s[18:19], 0, v[16:17]
	v_lshl_add_u64 v[12:13], s[18:19], 0, v[18:19]
	v_lshl_add_u64 v[20:21], s[18:19], 0, v[14:15]
	v_lshl_add_u64 v[32:33], s[18:19], 0, v[30:31]
	global_load_ushort v40, v[4:5], off
	global_load_ushort v41, v[8:9], off
	global_load_ushort v42, v[10:11], off
	global_load_ushort v43, v[12:13], off
	global_load_ushort v44, v[20:21], off
	global_load_ushort v45, v[24:25], off
	global_load_ushort v46, v[28:29], off
	global_load_ushort v47, v[32:33], off
	v_lshl_add_u64 v[4:5], s[14:15], 0, v[30:31]
	v_lshl_add_u64 v[24:25], s[14:15], 0, v[26:27]
	v_lshl_add_u64 v[28:29], s[14:15], 0, v[22:23]
	v_lshl_add_u64 v[22:23], s[16:17], 0, v[22:23]
	v_lshl_add_u64 v[20:21], s[16:17], 0, v[30:31]
	v_lshl_add_u64 v[26:27], s[16:17], 0, v[26:27]
	v_lshl_add_u64 v[30:31], s[14:15], 0, v[14:15]
	v_lshl_add_u64 v[32:33], s[16:17], 0, v[14:15]
	global_load_ushort v12, v[4:5], off
	global_load_ushort v8, v[20:21], off
	global_load_ushort v13, v[24:25], off
	global_load_ushort v9, v[26:27], off
	global_load_ushort v14, v[28:29], off
	global_load_ushort v10, v[22:23], off
	global_load_ushort v15, v[30:31], off
	global_load_ushort v11, v[32:33], off
	v_lshl_add_u64 v[4:5], s[14:15], 0, v[18:19]
	v_lshl_add_u64 v[18:19], s[16:17], 0, v[18:19]
	v_lshl_add_u64 v[22:23], s[14:15], 0, v[6:7]
	v_lshl_add_u64 v[6:7], s[16:17], 0, v[6:7]
	v_lshl_add_u64 v[24:25], s[14:15], 0, v[2:3]
	v_lshl_add_u64 v[2:3], s[16:17], 0, v[2:3]
	v_ashrrev_i32_e32 v1, 31, v0
	v_lshl_add_u64 v[20:21], s[14:15], 0, v[16:17]
	v_lshl_add_u64 v[16:17], s[16:17], 0, v[16:17]
	global_load_ushort v121, v[4:5], off
	global_load_ushort v152, v[18:19], off
	global_load_ushort v115, v[20:21], off
	global_load_ushort v154, v[16:17], off
	global_load_ushort v119, v[22:23], off
	global_load_ushort v155, v[6:7], off
	global_load_ushort v132, v[24:25], off
	global_load_ushort v156, v[2:3], off
	v_lshlrev_b64 v[2:3], 11, v[0:1]
	v_or_b32_e32 v6, 1, v0
	v_or_b32_e32 v18, 2, v0
	v_or_b32_e32 v22, 3, v0
	v_or_b32_e32 v26, 4, v0
	v_or_b32_e32 v30, 5, v0
	v_or_b32_e32 v34, 6, v0
	v_or_b32_e32 v0, 7, v0
	v_ashrrev_i32_e32 v7, 31, v6
	v_ashrrev_i32_e32 v19, 31, v18
	v_ashrrev_i32_e32 v23, 31, v22
	v_ashrrev_i32_e32 v27, 31, v26
	v_ashrrev_i32_e32 v31, 31, v30
	v_ashrrev_i32_e32 v35, 31, v34
	v_ashrrev_i32_e32 v1, 31, v0
	v_or_b32_e32 v2, v2, v38
	v_lshlrev_b64 v[6:7], 11, v[6:7]
	v_lshlrev_b64 v[18:19], 11, v[18:19]
	v_lshlrev_b64 v[22:23], 11, v[22:23]
	v_lshlrev_b64 v[26:27], 11, v[26:27]
	v_lshlrev_b64 v[30:31], 11, v[30:31]
	v_lshlrev_b64 v[34:35], 11, v[34:35]
	v_lshlrev_b64 v[0:1], 11, v[0:1]
	v_lshl_add_u64 v[4:5], s[18:19], 0, v[2:3]
	v_or_b32_e32 v6, v6, v38
	v_or_b32_e32 v18, v18, v38
	v_or_b32_e32 v22, v22, v38
	v_or_b32_e32 v26, v26, v38
	v_or_b32_e32 v30, v30, v38
	v_or_b32_e32 v34, v34, v38
	v_or_b32_e32 v0, v0, v38
	v_lshl_add_u64 v[16:17], s[18:19], 0, v[6:7]
	v_lshl_add_u64 v[20:21], s[18:19], 0, v[18:19]
	v_lshl_add_u64 v[24:25], s[18:19], 0, v[22:23]
	v_lshl_add_u64 v[28:29], s[18:19], 0, v[26:27]
	v_lshl_add_u64 v[32:33], s[18:19], 0, v[30:31]
	v_lshl_add_u64 v[36:37], s[18:19], 0, v[34:35]
	v_lshl_add_u64 v[38:39], s[18:19], 0, v[0:1]
	global_load_ushort v48, v[4:5], off
	global_load_ushort v49, v[16:17], off
	global_load_ushort v50, v[20:21], off
	global_load_ushort v51, v[24:25], off
	global_load_ushort v52, v[28:29], off
	global_load_ushort v53, v[32:33], off
	global_load_ushort v54, v[36:37], off
	global_load_ushort v55, v[38:39], off
	v_lshl_add_u64 v[4:5], s[14:15], 0, v[0:1]
	v_lshl_add_u64 v[0:1], s[16:17], 0, v[0:1]
	v_lshl_add_u64 v[16:17], s[14:15], 0, v[34:35]
	v_lshl_add_u64 v[20:21], s[16:17], 0, v[34:35]
	v_lshl_add_u64 v[24:25], s[14:15], 0, v[30:31]
	v_lshl_add_u64 v[28:29], s[16:17], 0, v[30:31]
; #define LAS __attribute__((address_space(3)))
; __device__ __forceinline__ void hgrn_c_compute(Ctx& X, int u, const RawC& R) {
;     const int hd = u & 7, c = u >> 3, t0 = c * 64;
;     const int tid = X.tid, seg = tid >> 7, k = tid & 127, lane = X.lane, w = X.wave, r = lane & 31, h = lane >> 5;
;     LAS bf16_t* QH = (LAS bf16_t*)(X.lds);
;     LAS bf16_t* QT = (LAS bf16_t*)(X.lds + 17408);
;     LAS bf16_t* KT2 = (LAS bf16_t*)(X.lds + 34816);
;     LAS bf16_t* VT = (LAS bf16_t*)(X.lds + 52224);
;     LAS bf16_t* AM = (LAS bf16_t*)(X.lds + 70656);
;     LAS float* OF = (LAS float*)(X.lds + 79872);
;     LAS float* SEG = (LAS float*)(X.lds + 113664);
;     const bf16_t* HG = (const bf16_t*)(X.ws + WS_PROJ) + 6 * TSZ;
;     const int tt2 = w & 1, vt2 = w >> 1;
;     bf16x8 sfr[8];
;     {
;         const bf16_t* sb = (const bf16_t*)(X.ws + WS_SBUF) + (size_t)u * 16384 + (32 * vt2 + r) * 128 + 8 * h;
; #pragma unroll
;         for (int kk = 0; kk < 8; ++kk) sfr[kk] = *(const bf16x8*)(sb + 16 * kk);
;     }
;     const int tn = tid >> 3, sub = tid & 7;
;     const u32x4 g0 = *(const u32x4*)(HG + (size_t)(t0 + tn) * 1024 + hd * 128 + 16 * sub), g1 = *(const u32x4*)(HG + (size_t)(t0 + tn) * 1024 + hd * 128 + 16 * sub + 8);
	v_lshl_add_u64 v[30:31], s[14:15], 0, v[26:27]
	v_lshl_add_u64 v[26:27], s[16:17], 0, v[26:27]
	global_load_ushort v149, v[4:5], off
	global_load_ushort v162, v[0:1], off
	global_load_ushort v150, v[16:17], off
	global_load_ushort v163, v[20:21], off
	global_load_ushort v151, v[24:25], off
	global_load_ushort v160, v[28:29], off
	global_load_ushort v153, v[30:31], off
	global_load_ushort v161, v[26:27], off
	v_lshl_add_u64 v[0:1], s[14:15], 0, v[22:23]
	v_lshl_add_u64 v[4:5], s[16:17], 0, v[22:23]
	v_lshl_add_u64 v[16:17], s[14:15], 0, v[18:19]
	v_lshl_add_u64 v[18:19], s[16:17], 0, v[18:19]
	v_lshl_add_u64 v[20:21], s[14:15], 0, v[6:7]
	v_lshl_add_u64 v[6:7], s[16:17], 0, v[6:7]
	v_lshl_add_u64 v[22:23], s[14:15], 0, v[2:3]
	v_lshl_add_u64 v[2:3], s[16:17], 0, v[2:3]
	global_load_ushort v157, v[0:1], off
	global_load_ushort v165, v[4:5], off
	global_load_ushort v158, v[16:17], off
	global_load_ushort v166, v[18:19], off
	global_load_ushort v159, v[20:21], off
	global_load_ushort v167, v[6:7], off
	global_load_ushort v164, v[22:23], off
	global_load_ushort v168, v[2:3], off
	s_add_u32 s20, s90, 0x17700000
	v_readlane_b32 s30, v245, 21
	s_addc_u32 s21, s91, 0
	s_lshr_b32 s22, s30, 7
	s_movk_i32 s2, 0xff
	s_lshl_b32 s28, s22, 5
	s_add_i32 s0, 0, 0x1bc00
	v_cmp_lt_u32_e64 s[4:5], s2, v209
	s_movk_i32 s2, 0x17f
	v_cmp_lt_u32_e64 s[6:7], s2, v209
	s_movk_i32 s2, 0x1ff
	s_cmpk_lt_u32 s30, 0x100
	v_cmp_lt_u32_e64 s[8:9], s2, v209
	s_cselect_b64 s[24:25], -1, 0
	s_lshr_b32 s2, s30, 1
	s_and_b32 s37, s2, 32
	s_cmp_lg_u32 s22, 1
	v_lshrrev_b32_e32 v0, 7, v209
	v_lshrrev_b32_e32 v1, 5, v208
	v_lshlrev_b32_e32 v3, 4, v209
	s_cselect_b64 s[2:3], -1, 0
	s_bitcmp1_b32 s30, 6
	v_and_b32_e32 v72, 31, v209
	v_and_b32_e32 v16, 0x70, v3
	v_mul_u32_u24_e32 v3, 0x880, v0
	v_lshlrev_b32_e32 v20, 5, v0
	s_cselect_b64 s[10:11], -1, 0
	v_lshlrev_b32_e32 v0, 4, v1
	v_or_b32_e32 v2, s28, v72
	s_or_b64 s[26:27], s[2:3], s[10:11]
	v_add_u32_e32 v58, 0, v0
	s_movk_i32 s10, 0x110
	v_mad_u64_u32 v[60:61], s[2:3], v2, s10, v[58:59]
	s_add_i32 s2, 0, 0x11400
	s_lshl_b32 s3, s22, 6
	s_movk_i32 s29, 0x90
	s_add_i32 s3, s2, s3
	v_lshl_add_u32 v81, v1, 3, s3
	v_add_u32_e32 v96, s2, v0
	v_mad_u64_u32 v[62:63], s[2:3], v2, s29, v[58:59]
	s_add_i32 s3, 0, 0x13800
	v_mul_u32_u24_e32 v0, 0x210, v70
	v_lshlrev_b32_e32 v56, 2, v16
	v_add3_u32 v97, s3, v0, v56
	v_mbcnt_lo_u32_b32 v0, -1, 0
	v_mbcnt_hi_u32_b32 v0, -1, v0
	v_and_b32_e32 v2, 64, v0
	v_lshlrev_b32_e32 v78, 2, v1
	v_xor_b32_e32 v1, 1, v0
	v_add_u32_e32 v2, 64, v2
	v_readlane_b32 s35, v245, 1
	s_and_b32 s2, s30, 0xffffff80
	v_cmp_lt_i32_e32 vcc, v1, v2
	s_add_i32 s2, s3, s2
	v_readlane_b32 s56, v245, 5
	v_cndmask_b32_e32 v1, v0, v1, vcc
	s_ashr_i32 s35, s34, 31
	v_and_b32_e32 v18, 32, v209
	v_mov_b32_e32 v57, 0
	v_lshl_add_u32 v63, v72, 2, s2
	v_lshlrev_b32_e32 v98, 2, v1
	v_xor_b32_e32 v1, 2, v0
	v_readlane_b32 s57, v245, 6
	s_lshl_b64 s[2:3], s[34:35], 15
	v_lshrrev_b32_e32 v18, 1, v18
	v_lshlrev_b32_e32 v21, 7, v72
	v_cmp_lt_i32_e32 vcc, v1, v2
	v_lshl_add_u64 v[64:65], s[56:57], 0, v[56:57]
	v_or_b32_e32 v18, s2, v18
	v_mov_b32_e32 v19, s3
	v_lshl_or_b32 v56, s22, 12, v21
	v_cndmask_b32_e32 v1, v0, v1, vcc
	v_lshl_add_u64 v[18:19], v[56:57], 1, v[18:19]
	v_lshlrev_b32_e32 v99, 2, v1
	v_xor_b32_e32 v1, 4, v0
	v_lshl_add_u64 v[18:19], s[90:91], 0, v[18:19]
	s_mov_b64 s[2:3], 0xb700080
	v_cmp_lt_i32_e32 vcc, v1, v2
	v_lshl_add_u64 v[66:67], v[18:19], 0, s[2:3]
	s_ashr_i32 s3, s94, 31
	s_mov_b32 s2, s94
	v_lshl_add_u32 v73, v209, 2, s0
	v_lshl_add_u32 v74, v59, 2, s0
	s_movk_i32 s0, 0x80
	v_or_b32_e32 v3, v3, v59
	v_mad_u32_u24 v17, v59, s29, 0
	v_or_b32_e32 v76, s37, v72
	v_or_b32_e32 v80, s28, v78
	v_cndmask_b32_e32 v0, v0, v1, vcc
	s_mov_b32 s39, 0x5040100
	s_lshl_b64 s[28:29], s[2:3], 15
	s_mov_b32 s3, 0x800000
	s_mov_b32 s2, s34
	s_mov_b32 s23, 0
	v_cmp_gt_u32_e64 s[0:1], s0, v209
	v_lshl_add_u32 v75, v3, 1, 0
	v_mul_u32_u24_e32 v77, 0x90, v76
	v_mul_u32_u24_e32 v61, 0x110, v76
	v_mad_u32_u24 v79, v76, s10, v58
	v_or_b32_e32 v82, 2, v80
	v_or_b32_e32 v83, 3, v80
	v_or_b32_e32 v84, 8, v80
	v_or_b32_e32 v85, 9, v80
	v_or_b32_e32 v86, 10, v80
	v_or_b32_e32 v87, 11, v80
	v_or_b32_e32 v88, 16, v80
	v_or_b32_e32 v89, 17, v80
	v_or_b32_e32 v90, 18, v80
	v_or_b32_e32 v91, 19, v80
	v_or_b32_e32 v92, 24, v80
	v_or_b32_e32 v93, 25, v80
	v_or_b32_e32 v94, 26, v80
	v_or_b32_e32 v95, 27, v80
	s_movk_i32 s38, 0x210
	v_lshlrev_b32_e32 v100, 2, v0
	v_readlane_b32 s58, v245, 7
	v_readlane_b32 s59, v245, 8
	v_readlane_b32 s60, v245, 9
	v_readlane_b32 s61, v245, 10
	v_readlane_b32 s62, v245, 11
	v_readlane_b32 s63, v245, 12
	v_readlane_b32 s64, v245, 13
	v_readlane_b32 s65, v245, 14
	v_readlane_b32 s66, v245, 15
	v_readlane_b32 s67, v245, 16
	v_readlane_b32 s68, v245, 17
	v_readlane_b32 s69, v245, 18
	v_readlane_b32 s70, v245, 19
	v_readlane_b32 s71, v245, 20
	v_mul_u32_u24_e32 v101, 0x90, v72
	v_mul_u32_u24_e32 v102, 0x110, v72
	s_waitcnt vmcnt(22)
	v_perm_b32 v0, v49, v48, s39
	s_waitcnt vmcnt(20)
	v_perm_b32 v1, v51, v50, s39
	s_waitcnt vmcnt(18)
	v_perm_b32 v2, v53, v52, s39
	s_waitcnt vmcnt(16)
	v_perm_b32 v3, v55, v54, s39
	v_perm_b32 v4, v41, v40, s39
	v_perm_b32 v5, v43, v42, s39
	v_perm_b32 v6, v45, v44, s39
	v_perm_b32 v7, v47, v46, s39
	s_lshl_b32 s40, s94, 7
	v_lshlrev_b32_e32 v56, 1, v16
	v_add_u32_e32 v103, v17, v20
	v_mov_b32_e32 v104, 0x358637bd
	s_mov_b64 s[30:31], 0x7700800
	s_mov_b32 s41, 0x7700000
	v_writelane_b32 v245, s2, 0
	s_mov_b32 s42, s34
	s_nop 0
	v_writelane_b32 v245, s3, 1
	s_waitcnt vmcnt(0)
	v_lshrrev_b32_e32 v203, 6, v209
	v_and_b32_e32 v206, 63, v209
	v_lshrrev_b32_e32 v207, 4, v206
	v_and_b32_e32 v204, 15, v206
	v_xor_b32_e32 v204, v204, v207
	v_lshlrev_b32_e32 v204, 4, v204
	v_lshl_add_u32 v204, v207, 8, v204
	v_lshl_add_u32 v204, v203, 12, v204
	v_readfirstlane_b32 s72, v203
	v_lshrrev_b32_e32 v205, 1, v203
	v_and_b32_e32 v207, 31, v206
	v_lshl_add_u32 v207, v205, 5, v207
	v_lshlrev_b32_e32 v207, 8, v207
	v_lshrrev_b32_e32 v206, 5, v206
	v_lshl_add_u32 v207, v206, 4, v207
	v_add_u32_e32 v207, 0x80, v207
	s_lshl_b32 s72, s72, 12
	s_add_i32 s72, s72, 0x1c800
	v_mov_b32_e32 v194, v204
	v_sub_u32_e32 v194, v194, v207
	v_ashrrev_i32_e32 v195, 31, v194
	v_xor_b32_e32 v196, 0x40, v204
	v_add_u32_e32 v196, 0x400, v196
	v_sub_u32_e32 v196, v196, v207
	v_ashrrev_i32_e32 v197, 31, v196
	v_xor_b32_e32 v198, 0x80, v204
	v_add_u32_e32 v198, 0x800, v198
	v_sub_u32_e32 v198, v198, v207
	v_ashrrev_i32_e32 v199, 31, v198
	v_xor_b32_e32 v200, 0xc0, v204
	v_add_u32_e32 v200, 0xc00, v200
	v_sub_u32_e32 v200, v200, v207
	v_ashrrev_i32_e32 v201, 31, v200
	v_and_b32_e32 v202, 63, v209
	v_and_b32_e32 v204, 15, v202
	v_xor_b32_e32 v204, v204, v206
	v_and_b32_e32 v202, 31, v202
	v_lshlrev_b32_e32 v202, 8, v202
	v_lshl_add_u32 v202, v204, 4, v202
	v_lshl_add_u32 v202, v205, 13, v202
	v_add_u32_e32 v202, 0x1c800, v202
	s_branch .LBB0_733

; #define LAS __attribute__((address_space(3)))
; __device__ __forceinline__ int crow(int reg, int h) { return (reg & 3) + 8 * (reg >> 2) + 4 * h; }
; #define MFMA32(a, b, c) __builtin_amdgcn_mfma_f32_32x32x16_bf16((a), (b), (c), 0, 0, 0)
; __device__ __forceinline__ void hgrn_c_compute(Ctx& X, int u, const RawC& R) {
;     ...
;     {
;         f32x16 acc;
; #pragma unroll
;         for (int i = 0; i < 16; ++i) acc[i] = 0.f;
; #pragma unroll
;         for (int kk = 0; kk < 8; ++kk) {
;             const bf16x8 af = *(const LAS bf16x8*)(QH + (32 * tt2 + r) * 136 + 16 * kk + 8 * h);
;             acc = MFMA32(af, sfr[kk], acc);
;         }
; #pragma unroll
;         for (int ks = 0; ks < 4; ++ks) {
;             const bf16x8 af = *(const LAS bf16x8*)(AM + (32 * tt2 + r) * 72 + 16 * ks + 8 * h);
;             const bf16x8 bfr = *(const LAS bf16x8*)(VT + (32 * vt2 + r) * 72 + 16 * ks + 8 * h);
;             acc = MFMA32(af, bfr, acc);
;         }
; #pragma unroll
;         for (int i = 0; i < 16; ++i) OF[(32 * tt2 + crow(i, h)) * 132 + 32 * vt2 + r] = acc[i];
;     }
.LBB0_732:
	v_add_u32_e32 v119, v58, v119
	s_waitcnt vmcnt(2) lgkmcnt(0)
	s_barrier
	ds_read_b128 v[52:55], v202
	v_xor_b32_e32 v203, 0x20, v202
	ds_read_b128 v[48:51], v203
	v_xor_b32_e32 v203, 0x40, v202
	ds_read_b128 v[44:47], v203
	v_xor_b32_e32 v203, 0x60, v202
	ds_read_b128 v[40:43], v203
	v_xor_b32_e32 v203, 0x80, v202
	ds_read_b128 v[36:39], v203
	v_xor_b32_e32 v203, 0xa0, v202
	ds_read_b128 v[32:35], v203
	v_xor_b32_e32 v203, 0xc0, v202
	ds_read_b128 v[24:27], v203
	v_xor_b32_e32 v203, 0xe0, v202
	ds_read_b128 v[20:23], v203
	ds_read_b128 v[0:3], v119
	ds_read_b128 v[150:153], v119 offset:32
	s_waitcnt lgkmcnt(1)
	v_mfma_f32_32x32x16_bf16 v[0:15], v[0:3], v[52:55], 0
	v_add_u32_e32 v115, v96, v115
	s_waitcnt vmcnt(1)
	v_lshlrev_b32_e32 v174, 16, v16
	v_and_b32_e32 v175, 0xffff0000, v16
	v_lshlrev_b32_e32 v176, 16, v19
	v_and_b32_e32 v177, 0xffff0000, v19
	v_add_u32_e32 v121, s2, v78
	s_waitcnt vmcnt(0)
	v_lshlrev_b32_e32 v170, 16, v28
	s_waitcnt lgkmcnt(0)
	v_mfma_f32_32x32x16_bf16 v[0:15], v[150:153], v[48:51], v[0:15]
	ds_read_b128 v[48:51], v119 offset:64
	ds_read_b128 v[52:55], v119 offset:96
	v_and_b32_e32 v171, 0xffff0000, v28
	v_lshlrev_b32_e32 v172, 16, v29
	v_and_b32_e32 v173, 0xffff0000, v29
	s_add_i32 s54, s54, s50
	s_add_i32 s36, s36, s40
	v_lshl_add_u64 v[66:67], v[66:67], 0, s[28:29]
	s_waitcnt lgkmcnt(1)
	v_mfma_f32_32x32x16_bf16 v[0:15], v[48:51], v[44:47], v[0:15]
	v_mov_b32_e32 v168, v114
	v_mov_b32_e32 v167, v112
	v_mov_b32_e32 v166, v113
	v_mov_b32_e32 v165, v122
	v_mov_b32_e32 v161, v123
	v_mov_b32_e32 v160, v124
	v_mov_b32_e32 v163, v128
	s_waitcnt lgkmcnt(0)
	v_mfma_f32_32x32x16_bf16 v[0:15], v[52:55], v[40:43], v[0:15]
	ds_read_b128 v[40:43], v119 offset:128
	ds_read_b128 v[44:47], v119 offset:160
	v_mov_b32_e32 v162, v129
	v_mov_b32_e32 v156, v137
	v_mov_b32_e32 v155, v138
	v_mov_b32_e32 v154, v139
	v_mov_b32_e32 v152, v148
	v_mov_b32_e32 v164, v105
	s_waitcnt lgkmcnt(1)
	v_mfma_f32_32x32x16_bf16 v[0:15], v[40:43], v[36:39], v[0:15]
	ds_read_b128 v[36:39], v62 offset:52224
	ds_read_b128 v[40:43], v62 offset:52256
	ds_read_b128 v[48:51], v119 offset:192
	v_mov_b32_e32 v159, v106
	v_mov_b32_e32 v158, v107
	v_mov_b32_e32 v157, v108
	v_mov_b32_e32 v153, v109
	v_mov_b32_e32 v151, v116
	v_mov_b32_e32 v150, v110
	s_waitcnt lgkmcnt(3)
	v_mfma_f32_32x32x16_bf16 v[0:15], v[44:47], v[32:35], v[0:15]
	ds_read_b128 v[32:35], v62 offset:52288
	ds_read_b128 v[44:47], v62 offset:52320
	ds_read_b128 v[52:55], v119 offset:224
	v_mov_b32_e32 v149, v111
	v_mov_b32_e32 v132, v118
	v_mov_b32_e32 v119, v120
	s_waitcnt lgkmcnt(3)
	v_mfma_f32_32x32x16_bf16 v[0:15], v[48:51], v[24:27], v[0:15]
	ds_read_b128 v[24:27], v115
	v_lshlrev_b32_e32 v48, 16, v30
	v_and_b32_e32 v49, 0xffff0000, v30
	v_lshlrev_b32_e32 v50, 16, v31
	v_and_b32_e32 v51, 0xffff0000, v31
	s_waitcnt lgkmcnt(1)
	v_mfma_f32_32x32x16_bf16 v[0:15], v[52:55], v[20:23], v[0:15]
	v_lshlrev_b32_e32 v52, 16, v17
	v_and_b32_e32 v53, 0xffff0000, v17
	v_lshlrev_b32_e32 v54, 16, v18
	v_and_b32_e32 v55, 0xffff0000, v18
	ds_read_b128 v[16:19], v115 offset:32
	ds_read_b128 v[20:23], v115 offset:64
	s_waitcnt lgkmcnt(2)
	v_mfma_f32_32x32x16_bf16 v[0:15], v[24:27], v[36:39], v[0:15]
	v_mad_i32_i24 v24, v121, s38, v63
	v_add_u32_e32 v25, 0x2400, v24
	v_add_u32_e32 v26, 0x3000, v24
	v_add_u32_e32 v27, 0x3400, v24
	v_lshlrev_b64 v[36:37], 12, v[68:69]
	v_lshl_add_u64 v[36:37], s[90:91], 0, v[36:37]
	v_lshl_add_u64 v[36:37], v[36:37], 0, s[22:23]
	s_waitcnt lgkmcnt(1)
	v_mfma_f32_32x32x16_bf16 v[0:15], v[16:19], v[40:43], v[0:15]
	ds_read_b128 v[16:19], v115 offset:96
	v_lshl_add_u64 v[36:37], v[36:37], 0, v[56:57]
	v_mov_b32_e32 v115, v117
	v_mov_b32_e32 v121, v131
	s_waitcnt lgkmcnt(1)
	v_mfma_f32_32x32x16_bf16 v[0:15], v[20:23], v[32:35], v[0:15]
	v_add_u32_e32 v20, 0x400, v24
	v_add_u32_e32 v21, 0x1000, v24
	v_add_u32_e32 v22, 0x1400, v24
	v_add_u32_e32 v23, 0x2000, v24
	s_waitcnt lgkmcnt(0)
	v_mfma_f32_32x32x16_bf16 v[0:15], v[16:19], v[44:47], v[0:15]
	s_nop 11
	ds_write2_b32 v24, v0, v1 offset1:132
	ds_write2_b32 v20, v2, v3 offset0:8 offset1:140
	ds_write2_b32 v21, v4, v5 offset0:32 offset1:164
	ds_write2_b32 v22, v6, v7 offset0:40 offset1:172
	ds_write2_b32 v23, v8, v9 offset0:64 offset1:196
	ds_write2_b32 v25, v10, v11 offset0:72 offset1:204
	ds_write2_b32 v26, v12, v13 offset0:96 offset1:228
	ds_write2_b32 v27, v14, v15 offset0:104 offset1:236
	s_waitcnt lgkmcnt(0)
	s_barrier
; #define LAS __attribute__((address_space(3)))
; __device__ __forceinline__ unsigned pk2_rne(float lo, float hi) { const f32x2_t f = {lo, hi}; return __builtin_bit_cast(unsigned, __builtin_convertvector(f, bf16x2_t)); }
; __device__ __forceinline__ float bflo(unsigned w) { return __uint_as_float(w << 16); }
; __device__ __forceinline__ float bfhi(unsigned w) { return __uint_as_float(w & 0xffff0000u); }
; __device__ __forceinline__ void hgrn_c_compute(Ctx& X, int u, const RawC& R) {
;     ...
;     {
;         float ov[16]; float ss = 0.f;
; #pragma unroll
;         for (int e = 0; e < 4; ++e) { const f32x4 q4 = *(const LAS f32x4*)(OF + tn * 132 + 16 * sub + 4 * e); ov[4 * e] = q4[0]; ov[4 * e + 1] = q4[1]; ov[4 * e + 2] = q4[2]; ov[4 * e + 3] = q4[3]; }
; #pragma unroll
;         for (int e = 0; e < 16; ++e) ss += ov[e] * ov[e];
;         ss += __shfl_xor(ss, 1); ss += __shfl_xor(ss, 2); ss += __shfl_xor(ss, 4);
;         const float rinv = rsqrtf(ss * (1.f / 128.f) + EPS);
;         const unsigned gw[8] = {g0.x, g0.y, g0.z, g0.w, g1.x, g1.y, g1.z, g1.w};
;         unsigned pw[8];
; #pragma unroll
;         for (int e = 0; e < 8; ++e) {
;             const float w0 = X.gnorm_w[16 * sub + 2 * e], w1 = X.gnorm_w[16 * sub + 2 * e + 1];
;             pw[e] = pk2_rne(ov[2 * e] * rinv * w0 * bflo(gw[e]), ov[2 * e + 1] * rinv * w1 * bfhi(gw[e]));
;         }
;         bf16_t* yp = (bf16_t*)(X.ws + WS_H) + (size_t)(t0 + tn) * D + 1024 + hd * 128 + 16 * sub;
;         *(u32x4*)(yp) = (u32x4){pw[0], pw[1], pw[2], pw[3]}; *(u32x4*)(yp + 8) = (u32x4){pw[4], pw[5], pw[6], pw[7]};
;     }
;     __syncthreads();
	global_load_dwordx4 v[0:3], v[64:65], off offset:16
	global_load_dwordx4 v[4:7], v[64:65], off
	global_load_dwordx4 v[12:15], v[64:65], off offset:48
	global_load_dwordx4 v[16:19], v[64:65], off offset:32
	ds_read_b128 v[20:23], v97
	ds_read_b128 v[24:27], v97 offset:32
	ds_read_b128 v[28:31], v97 offset:48
	ds_read_b128 v[32:35], v97 offset:16
	v_mov_b32_e32 v11, v147
	v_mov_b32_e32 v10, v146
	s_waitcnt lgkmcnt(3)
	v_mul_f32_e32 v46, v21, v21
	v_fmac_f32_e32 v46, v20, v20
	v_fmac_f32_e32 v46, v22, v22
	v_fmac_f32_e32 v46, v23, v23
	s_waitcnt lgkmcnt(0)
	v_fmac_f32_e32 v46, v32, v32
	v_fmac_f32_e32 v46, v33, v33
	v_fmac_f32_e32 v46, v34, v34
	v_pk_mul_f32 v[40:41], v[24:25], v[24:25]
	v_fmac_f32_e32 v46, v35, v35
	v_add_f32_e32 v40, v40, v46
	v_pk_mul_f32 v[38:39], v[26:27], v[26:27]
	v_add_f32_e32 v40, v41, v40
	v_add_f32_e32 v38, v38, v40
	v_pk_mul_f32 v[44:45], v[28:29], v[28:29]
	v_add_f32_e32 v38, v39, v38
	v_add_f32_e32 v38, v44, v38
	v_pk_mul_f32 v[42:43], v[30:31], v[30:31]
	v_add_f32_e32 v38, v45, v38
	v_add_f32_e32 v38, v42, v38
	v_add_f32_e32 v38, v43, v38
	ds_bpermute_b32 v39, v98, v38
	v_mov_b32_e32 v9, v144
	v_mov_b32_e32 v8, v145
	s_waitcnt lgkmcnt(0)
	v_add_f32_e32 v38, v38, v39
	ds_bpermute_b32 v39, v99, v38
	s_waitcnt lgkmcnt(0)
	v_add_f32_e32 v40, v38, v39
	ds_bpermute_b32 v41, v100, v40
	v_lshl_add_u64 v[38:39], v[36:37], 0, s[30:31]
	v_add_co_u32_e32 v36, vcc, s41, v36
	s_waitcnt lgkmcnt(0)
	v_add_f32_e32 v40, v40, v41
	v_fmamk_f32 v40, v40, 0x3c000000, v104
	v_mul_f32_e32 v41, 0x4b800000, v40
	v_cmp_gt_f32_e64 s[10:11], s3, v40
	v_addc_co_u32_e32 v37, vcc, 0, v37, vcc
	s_nop 0
	v_cndmask_b32_e64 v40, v40, v41, s[10:11]
	v_rsq_f32_e32 v40, v40
	s_andn2_b64 vcc, exec, s[34:35]
	v_mul_f32_e32 v41, 0x45800000, v40
	v_cndmask_b32_e64 v40, v40, v41, s[10:11]
	v_pk_mul_f32 v[20:21], v[20:21], v[40:41] op_sel_hi:[1,0]
	v_pk_mul_f32 v[22:23], v[22:23], v[40:41] op_sel_hi:[1,0]
	v_pk_mul_f32 v[32:33], v[32:33], v[40:41] op_sel_hi:[1,0]
	v_pk_mul_f32 v[34:35], v[34:35], v[40:41] op_sel_hi:[1,0]
	v_pk_mul_f32 v[24:25], v[24:25], v[40:41] op_sel_hi:[1,0]
	v_pk_mul_f32 v[26:27], v[26:27], v[40:41] op_sel_hi:[1,0]
	v_pk_mul_f32 v[28:29], v[28:29], v[40:41] op_sel_hi:[1,0]
	v_pk_mul_f32 v[30:31], v[30:31], v[40:41] op_sel_hi:[1,0]
	s_waitcnt vmcnt(3)
	v_pk_mul_f32 v[0:1], v[0:1], v[32:33]
	s_waitcnt vmcnt(2)
	v_pk_mul_f32 v[4:5], v[4:5], v[20:21]
	v_pk_mul_f32 v[6:7], v[6:7], v[22:23]
	v_pk_mul_f32 v[2:3], v[2:3], v[34:35]
	s_waitcnt vmcnt(0)
	v_pk_mul_f32 v[16:17], v[16:17], v[24:25]
	v_pk_mul_f32 v[18:19], v[18:19], v[26:27]
	v_pk_mul_f32 v[12:13], v[12:13], v[28:29]
	v_pk_mul_f32 v[14:15], v[14:15], v[30:31]
	v_pk_mul_f32 v[4:5], v[4:5], v[170:171]
	v_pk_mul_f32 v[6:7], v[6:7], v[172:173]
	v_pk_mul_f32 v[20:21], v[0:1], v[48:49]
	v_pk_mul_f32 v[22:23], v[2:3], v[50:51]
	v_pk_mul_f32 v[16:17], v[16:17], v[174:175]
	v_pk_mul_f32 v[18:19], v[18:19], v[52:53]
	v_pk_mul_f32 v[12:13], v[12:13], v[54:55]
	v_pk_mul_f32 v[14:15], v[14:15], v[176:177]
	v_cvt_pk_bf16_f32 v0, v4, v5
	v_cvt_pk_bf16_f32 v1, v6, v7
	v_cvt_pk_bf16_f32 v2, v20, v21
	v_cvt_pk_bf16_f32 v3, v22, v23
	v_cvt_pk_bf16_f32 v4, v16, v17
	v_cvt_pk_bf16_f32 v5, v18, v19
	v_cvt_pk_bf16_f32 v6, v12, v13
	v_cvt_pk_bf16_f32 v7, v14, v15
	global_store_dwordx4 v[36:37], v[0:3], off offset:2048
	global_store_dwordx4 v[38:39], v[4:7], off offset:16
	v_mov_b32_e32 v15, v130
	v_mov_b32_e32 v14, v125
	v_mov_b32_e32 v13, v126
	v_mov_b32_e32 v12, v127
	s_waitcnt vmcnt(2)
	v_perm_b32 v140, v214, v213, s39
	v_perm_b32 v141, v216, v215, s39
	v_perm_b32 v142, v218, v217, s39
	v_perm_b32 v143, v220, v219, s39
	v_perm_b32 v133, v222, v221, s39
	v_perm_b32 v134, v224, v223, s39
	v_perm_b32 v135, v211, v225, s39
	v_perm_b32 v136, v210, v212, s39
	v_mov_b32_e32 v0, v140
	v_mov_b32_e32 v1, v141
	v_mov_b32_e32 v2, v142
	v_mov_b32_e32 v3, v143
	v_mov_b32_e32 v4, v133
	v_mov_b32_e32 v5, v134
	v_mov_b32_e32 v6, v135
	v_mov_b32_e32 v7, v136
	s_barrier
	s_cbranch_vccz .LBB0_739

; __device__ __forceinline__ unsigned pk2_rne(float lo, float hi) { const f32x2_t f = {lo, hi}; return __builtin_bit_cast(unsigned, __builtin_convertvector(f, bf16x2_t)); }
; __device__ __forceinline__ float bf2f(unsigned short b) { return __uint_as_float(((unsigned)b) << 16); }
; __device__ __forceinline__ void hgrn_c_compute(Ctx& X, int u, const RawC& R) {
;     ...
;     const int tt2 = w & 1, vt2 = w >> 1;
;     bf16x8 sfr[8];
;     {
;         const bf16_t* sb = (const bf16_t*)(X.ws + WS_SBUF) + (size_t)u * 16384 + (32 * vt2 + r) * 128 + 8 * h;
; #pragma unroll
;         for (int kk = 0; kk < 8; ++kk) sfr[kk] = *(const bf16x8*)(sb + 16 * kk);
;     }
;     const int tn = tid >> 3, sub = tid & 7;
;     const u32x4 g0 = *(const u32x4*)(HG + (size_t)(t0 + tn) * 1024 + hd * 128 + 16 * sub), g1 = *(const u32x4*)(HG + (size_t)(t0 + tn) * 1024 + hd * 128 + 16 * sub + 8);
;     {
;         float lf[16], b[16]; float run = 0.f;
; #pragma unroll
;         for (int i = 0; i < 16; ++i) { lf[i] = bf2f(R.lf[i]); run += lf[i]; b[i] = run; }
;         SEG[seg * 128 + k] = run;
;         __syncthreads();
;         float off = 0.f;
; #pragma unroll
;         for (int s = 0; s < 4; ++s) { const float v = SEG[s * 128 + k]; off += (s < seg) ? v : 0.f; }
;         const float bmid = SEG[k] + SEG[128 + k];
;         unsigned pv[8];
; #pragma unroll
;         for (int i = 0; i < 16; ++i) {
;             const float bt = off + b[i]; const int t = 16 * seg + i; const float q = bf2f(R.q[i]);
;             const unsigned qh = pk2_rne(q * __expf(bt), q * __expf(bt - bmid));
;             const unsigned kk = pk2_rne((1.f - __expf(lf[i])) * __expf(bmid - bt), 0.f);
;             QH[t * 136 + k] = (bf16_t)(qh & 0xffffu); QT[t * 136 + k] = (bf16_t)(qh >> 16); KT2[t * 136 + k] = (bf16_t)(kk & 0xffffu);
.LBB0_736:
	v_lshlrev_b32_e32 v170, 16, v168
	v_add_f32_e32 v168, 0, v170
	v_lshlrev_b32_e32 v167, 16, v167
	v_add_f32_e32 v171, v168, v167
	v_lshlrev_b32_e32 v166, 16, v166
	v_add_f32_e32 v172, v171, v166
	v_lshlrev_b32_e32 v165, 16, v165
	v_add_f32_e32 v173, v172, v165
	v_lshlrev_b32_e32 v161, 16, v161
	v_add_f32_e32 v174, v173, v161
	v_lshlrev_b32_e32 v160, 16, v160
	v_add_f32_e32 v175, v174, v160
	v_lshlrev_b32_e32 v163, 16, v163
	v_add_f32_e32 v176, v175, v163
	v_lshlrev_b32_e32 v162, 16, v162
	v_add_f32_e32 v177, v176, v162
	v_lshlrev_b32_e32 v156, 16, v156
	v_add_f32_e32 v178, v177, v156
	v_lshlrev_b32_e32 v179, 16, v155
	s_and_b32 s2, s54, 0xffffffc0
	v_add_f32_e32 v180, v178, v179
	v_lshlrev_b32_e32 v181, 16, v154
	v_add_u32_e32 v68, s2, v70
	v_add_f32_e32 v182, v180, v181
	v_lshlrev_b32_e32 v183, 16, v152
	v_ashrrev_i32_e32 v69, 31, v68
	v_add_f32_e32 v184, v182, v183
	v_lshlrev_b32_e32 v185, 16, v11
	v_lshlrev_b64 v[16:17], 11, v[68:69]
	s_and_b32 s2, s36, 0x380
	v_add_f32_e32 v186, v184, v185
	v_lshlrev_b32_e32 v187, 16, v10
	v_lshl_add_u64 v[16:17], s[20:21], 0, v[16:17]
	s_lshl_b32 s22, s2, 1
	v_add_f32_e32 v188, v186, v187
	v_lshlrev_b32_e32 v189, 16, v9
	v_lshl_add_u64 v[16:17], v[16:17], 0, s[22:23]
	v_add_f32_e32 v190, v188, v189
	v_lshlrev_b32_e32 v192, 16, v8
	v_lshl_add_u64 v[28:29], v[16:17], 0, v[56:57]
	v_add_f32_e32 v193, v190, v192
	s_mov_b32 m0, s72
	v_lshl_add_u64 v[204:205], v[66:67], 0, v[194:195]
	global_load_lds_dwordx4 v[204:205], off
	s_add_i32 m0, s72, 0x400
	v_lshl_add_u64 v[204:205], v[66:67], 0, v[196:197]
	global_load_lds_dwordx4 v[204:205], off
	s_add_i32 m0, s72, 0x800
	v_lshl_add_u64 v[204:205], v[66:67], 0, v[198:199]
	global_load_lds_dwordx4 v[204:205], off
	s_add_i32 m0, s72, 0xc00
	v_lshl_add_u64 v[204:205], v[66:67], 0, v[200:201]
	global_load_lds_dwordx4 v[204:205], off
	global_load_dwordx4 v[16:19], v[28:29], off offset:16
	s_nop 0
	global_load_dwordx4 v[28:31], v[28:29], off
	ds_write_b32 v73, v193
	s_waitcnt lgkmcnt(0)
	s_barrier
	ds_read2st64_b32 v[8:9], v74 offset1:2
	ds_read2st64_b32 v[10:11], v74 offset0:4 offset1:6
	s_andn2_b64 vcc, exec, s[24:25]
	s_mov_b32 s2, s37
	s_waitcnt lgkmcnt(1)
	v_add_f32_e32 v152, 0, v8
	v_cndmask_b32_e64 v152, v152, 0, s[0:1]
	v_cndmask_b32_e64 v154, 0, v9, s[4:5]
	v_add_f32_e32 v152, v152, v154
	s_waitcnt lgkmcnt(0)
	v_cndmask_b32_e64 v10, 0, v10, s[6:7]
	v_add_f32_e32 v10, v152, v10
	v_cndmask_b32_e64 v11, 0, v11, s[8:9]
	v_add_f32_e32 v10, v10, v11
	v_mov_b32_e32 v169, v8
	v_mov_b32_e32 v11, v9
	v_pk_add_f32 v[8:9], v[168:169], v[10:11]
	v_lshlrev_b32_e32 v152, 16, v164
	v_mul_f32_e32 v11, 0x3fb8aa3b, v8
	v_exp_f32_e32 v154, v11
	v_sub_f32_e32 v11, v8, v9
	v_mul_f32_e32 v11, 0x3fb8aa3b, v11
	v_exp_f32_e32 v155, v11
	v_mul_f32_e32 v11, 0x3fb8aa3b, v170
	v_sub_f32_e32 v8, v9, v8
	v_exp_f32_e32 v11, v11
	v_mul_f32_e32 v8, 0x3fb8aa3b, v8
	v_exp_f32_e32 v8, v8
	v_pk_mul_f32 v[154:155], v[154:155], v[152:153] op_sel_hi:[1,0]
	v_sub_f32_e32 v11, 1.0, v11
	v_cvt_pk_bf16_f32 v152, v154, v155
	v_mul_f32_e32 v8, v11, v8
	v_add_f32_e32 v11, v171, v10
	v_cvt_pk_bf16_f32 v8, v8, s0
	ds_write_b16 v75, v152
	ds_write_b16_d16_hi v75, v152 offset:17408
	ds_write_b16 v75, v8 offset:34816
	v_mul_f32_e32 v152, 0x3fb8aa3b, v11
	v_exp_f32_e32 v154, v152
	v_sub_f32_e32 v152, v11, v9
	v_mul_f32_e32 v152, 0x3fb8aa3b, v152
	v_exp_f32_e32 v155, v152
	v_mul_f32_e32 v152, 0x3fb8aa3b, v167
	v_sub_f32_e32 v11, v9, v11
	v_exp_f32_e32 v152, v152
	v_mul_f32_e32 v11, 0x3fb8aa3b, v11
	v_exp_f32_e32 v11, v11
	v_lshlrev_b32_e32 v8, 16, v159
	v_sub_f32_e32 v152, 1.0, v152
	v_pk_mul_f32 v[154:155], v[154:155], v[8:9] op_sel_hi:[1,0]
	v_mul_f32_e32 v11, v152, v11
	v_cvt_pk_bf16_f32 v8, v154, v155
	v_cvt_pk_bf16_f32 v11, v11, s0
	ds_write_b16 v75, v8 offset:272
	ds_write_b16_d16_hi v75, v8 offset:17680
	ds_write_b16 v75, v11 offset:35088
	v_add_f32_e32 v11, v172, v10
	v_mul_f32_e32 v152, 0x3fb8aa3b, v11
	v_exp_f32_e32 v154, v152
	v_sub_f32_e32 v152, v11, v9
	v_mul_f32_e32 v152, 0x3fb8aa3b, v152
	v_exp_f32_e32 v155, v152
	v_mul_f32_e32 v152, 0x3fb8aa3b, v166
	v_sub_f32_e32 v11, v9, v11
	v_exp_f32_e32 v152, v152
	v_mul_f32_e32 v11, 0x3fb8aa3b, v11
	v_exp_f32_e32 v11, v11
	v_lshlrev_b32_e32 v8, 16, v158
	v_sub_f32_e32 v152, 1.0, v152
	v_pk_mul_f32 v[154:155], v[154:155], v[8:9] op_sel_hi:[1,0]
	v_mul_f32_e32 v11, v152, v11
	v_cvt_pk_bf16_f32 v8, v154, v155
	v_cvt_pk_bf16_f32 v11, v11, s0
	ds_write_b16 v75, v8 offset:544
	ds_write_b16_d16_hi v75, v8 offset:17952
	ds_write_b16 v75, v11 offset:35360
	v_add_f32_e32 v11, v173, v10
	v_mul_f32_e32 v152, 0x3fb8aa3b, v11
	v_exp_f32_e32 v154, v152
	v_sub_f32_e32 v152, v11, v9
	v_mul_f32_e32 v152, 0x3fb8aa3b, v152
	v_exp_f32_e32 v155, v152
	v_mul_f32_e32 v152, 0x3fb8aa3b, v165
	v_sub_f32_e32 v11, v9, v11
	v_exp_f32_e32 v152, v152
	v_mul_f32_e32 v11, 0x3fb8aa3b, v11
	v_exp_f32_e32 v11, v11
	v_lshlrev_b32_e32 v8, 16, v157
	v_sub_f32_e32 v152, 1.0, v152
	v_pk_mul_f32 v[154:155], v[154:155], v[8:9] op_sel_hi:[1,0]
	v_mul_f32_e32 v11, v152, v11
	v_cvt_pk_bf16_f32 v8, v154, v155
	v_cvt_pk_bf16_f32 v11, v11, s0
	ds_write_b16 v75, v8 offset:816
	ds_write_b16_d16_hi v75, v8 offset:18224
	ds_write_b16 v75, v11 offset:35632
	v_add_f32_e32 v11, v174, v10
	v_lshlrev_b32_e32 v8, 16, v153
	v_sub_f32_e32 v153, v11, v9
	v_mul_f32_e32 v152, 0x3fb8aa3b, v11
	v_mul_f32_e32 v153, 0x3fb8aa3b, v153
	v_exp_f32_e32 v152, v152
	v_exp_f32_e32 v153, v153
	v_mul_f32_e32 v154, 0x3fb8aa3b, v161
	v_sub_f32_e32 v11, v9, v11
	v_exp_f32_e32 v154, v154
	v_mul_f32_e32 v11, 0x3fb8aa3b, v11
	v_exp_f32_e32 v11, v11
	v_pk_mul_f32 v[152:153], v[152:153], v[8:9] op_sel_hi:[1,0]
	s_nop 0
; __device__ __forceinline__ unsigned pk2_rne(float lo, float hi) { const f32x2_t f = {lo, hi}; return __builtin_bit_cast(unsigned, __builtin_convertvector(f, bf16x2_t)); }
; __device__ __forceinline__ float bf2f(unsigned short b) { return __uint_as_float(((unsigned)b) << 16); }
; __device__ __forceinline__ void hgrn_c_compute(Ctx& X, int u, const RawC& R) {
;     ...
;         for (int i = 0; i < 16; ++i) {
;             const float bt = off + b[i]; const int t = 16 * seg + i; const float q = bf2f(R.q[i]);
;             const unsigned qh = pk2_rne(q * __expf(bt), q * __expf(bt - bmid));
;             const unsigned kk = pk2_rne((1.f - __expf(lf[i])) * __expf(bmid - bt), 0.f);
;             QH[t * 136 + k] = (bf16_t)(qh & 0xffffu); QT[t * 136 + k] = (bf16_t)(qh >> 16); KT2[t * 136 + k] = (bf16_t)(kk & 0xffffu);
;         }
	v_cvt_pk_bf16_f32 v8, v152, v153
	v_sub_f32_e32 v152, 1.0, v154
	v_mul_f32_e32 v11, v152, v11
	v_cvt_pk_bf16_f32 v11, v11, s0
	ds_write_b16 v75, v8 offset:1088
	ds_write_b16_d16_hi v75, v8 offset:18496
	ds_write_b16 v75, v11 offset:35904
	v_add_f32_e32 v11, v175, v10
	v_lshlrev_b32_e32 v8, 16, v151
	v_mul_f32_e32 v151, 0x3fb8aa3b, v11
	v_exp_f32_e32 v152, v151
	v_sub_f32_e32 v151, v11, v9
	v_mul_f32_e32 v151, 0x3fb8aa3b, v151
	v_exp_f32_e32 v153, v151
	v_mul_f32_e32 v151, 0x3fb8aa3b, v160
	v_sub_f32_e32 v11, v9, v11
	v_exp_f32_e32 v151, v151
	v_mul_f32_e32 v11, 0x3fb8aa3b, v11
	v_exp_f32_e32 v11, v11
	v_pk_mul_f32 v[152:153], v[152:153], v[8:9] op_sel_hi:[1,0]
	v_sub_f32_e32 v151, 1.0, v151
	v_cvt_pk_bf16_f32 v8, v152, v153
	v_mul_f32_e32 v11, v151, v11
	v_cvt_pk_bf16_f32 v11, v11, s0
	ds_write_b16 v75, v8 offset:1360
	ds_write_b16_d16_hi v75, v8 offset:18768
	ds_write_b16 v75, v11 offset:36176
	v_add_f32_e32 v11, v176, v10
	v_sub_f32_e32 v151, v11, v9
	v_lshlrev_b32_e32 v8, 16, v150
	v_mul_f32_e32 v150, 0x3fb8aa3b, v11
	v_mul_f32_e32 v151, 0x3fb8aa3b, v151
	v_exp_f32_e32 v150, v150
	v_exp_f32_e32 v151, v151
	v_mul_f32_e32 v152, 0x3fb8aa3b, v163
	v_sub_f32_e32 v11, v9, v11
	v_exp_f32_e32 v152, v152
	v_mul_f32_e32 v11, 0x3fb8aa3b, v11
	v_exp_f32_e32 v11, v11
	v_pk_mul_f32 v[150:151], v[150:151], v[8:9] op_sel_hi:[1,0]
	s_nop 0
	v_cvt_pk_bf16_f32 v8, v150, v151
	v_sub_f32_e32 v150, 1.0, v152
	v_mul_f32_e32 v11, v150, v11
	v_cvt_pk_bf16_f32 v11, v11, s0
	ds_write_b16 v75, v8 offset:1632
	ds_write_b16_d16_hi v75, v8 offset:19040
	ds_write_b16 v75, v11 offset:36448
	v_add_f32_e32 v11, v177, v10
	v_lshlrev_b32_e32 v8, 16, v149
	v_mul_f32_e32 v149, 0x3fb8aa3b, v11
	v_exp_f32_e32 v150, v149
	v_sub_f32_e32 v149, v11, v9
	v_mul_f32_e32 v149, 0x3fb8aa3b, v149
	v_exp_f32_e32 v151, v149
	v_mul_f32_e32 v149, 0x3fb8aa3b, v162
	v_sub_f32_e32 v11, v9, v11
	v_exp_f32_e32 v149, v149
	v_mul_f32_e32 v11, 0x3fb8aa3b, v11
	v_exp_f32_e32 v11, v11
	v_pk_mul_f32 v[150:151], v[150:151], v[8:9] op_sel_hi:[1,0]
	v_sub_f32_e32 v149, 1.0, v149
	v_cvt_pk_bf16_f32 v8, v150, v151
	v_mul_f32_e32 v11, v149, v11
	v_cvt_pk_bf16_f32 v11, v11, s0
	ds_write_b16 v75, v8 offset:1904
	ds_write_b16_d16_hi v75, v8 offset:19312
	ds_write_b16 v75, v11 offset:36720
	v_add_f32_e32 v11, v178, v10
	v_lshlrev_b32_e32 v8, 16, v132
	v_mul_f32_e32 v132, 0x3fb8aa3b, v11
	v_exp_f32_e32 v150, v132
	v_sub_f32_e32 v132, v11, v9
	v_mul_f32_e32 v132, 0x3fb8aa3b, v132
	v_exp_f32_e32 v151, v132
	v_mul_f32_e32 v132, 0x3fb8aa3b, v156
	v_sub_f32_e32 v11, v9, v11
	v_exp_f32_e32 v132, v132
	v_mul_f32_e32 v11, 0x3fb8aa3b, v11
	v_exp_f32_e32 v11, v11
	v_pk_mul_f32 v[150:151], v[150:151], v[8:9] op_sel_hi:[1,0]
	v_sub_f32_e32 v132, 1.0, v132
	v_cvt_pk_bf16_f32 v8, v150, v151
	v_mul_f32_e32 v11, v132, v11
	v_cvt_pk_bf16_f32 v11, v11, s0
	ds_write_b16 v75, v8 offset:2176
	ds_write_b16_d16_hi v75, v8 offset:19584
	ds_write_b16 v75, v11 offset:36992
	v_add_f32_e32 v11, v180, v10
	v_lshlrev_b32_e32 v8, 16, v119
	v_mul_f32_e32 v119, 0x3fb8aa3b, v11
	v_exp_f32_e32 v150, v119
	v_sub_f32_e32 v119, v11, v9
	v_mul_f32_e32 v119, 0x3fb8aa3b, v119
	v_exp_f32_e32 v151, v119
	v_mul_f32_e32 v119, 0x3fb8aa3b, v179
	v_sub_f32_e32 v11, v9, v11
	v_exp_f32_e32 v119, v119
	v_mul_f32_e32 v11, 0x3fb8aa3b, v11
	v_exp_f32_e32 v11, v11
	v_pk_mul_f32 v[150:151], v[150:151], v[8:9] op_sel_hi:[1,0]
	v_sub_f32_e32 v119, 1.0, v119
	v_cvt_pk_bf16_f32 v8, v150, v151
	v_mul_f32_e32 v11, v119, v11
	v_cvt_pk_bf16_f32 v11, v11, s0
	ds_write_b16 v75, v8 offset:2448
	ds_write_b16_d16_hi v75, v8 offset:19856
	ds_write_b16 v75, v11 offset:37264
	v_add_f32_e32 v11, v182, v10
	v_lshlrev_b32_e32 v8, 16, v115
	v_mul_f32_e32 v115, 0x3fb8aa3b, v11
	v_exp_f32_e32 v150, v115
	v_sub_f32_e32 v115, v11, v9
	v_mul_f32_e32 v115, 0x3fb8aa3b, v115
	v_exp_f32_e32 v151, v115
	v_mul_f32_e32 v115, 0x3fb8aa3b, v181
	v_sub_f32_e32 v11, v9, v11
	v_exp_f32_e32 v115, v115
	v_mul_f32_e32 v11, 0x3fb8aa3b, v11
	v_exp_f32_e32 v11, v11
	v_pk_mul_f32 v[150:151], v[150:151], v[8:9] op_sel_hi:[1,0]
	v_sub_f32_e32 v115, 1.0, v115
	v_cvt_pk_bf16_f32 v8, v150, v151
	v_mul_f32_e32 v11, v115, v11
; #define LAS __attribute__((address_space(3)))
; __device__ __forceinline__ unsigned pk2_rne(float lo, float hi) { const f32x2_t f = {lo, hi}; return __builtin_bit_cast(unsigned, __builtin_convertvector(f, bf16x2_t)); }
; __device__ __forceinline__ float bf2f(unsigned short b) { return __uint_as_float(((unsigned)b) << 16); }
; __device__ __forceinline__ void hgrn_c_compute(Ctx& X, int u, const RawC& R) {
;     ...
;         for (int i = 0; i < 16; ++i) {
;             const float bt = off + b[i]; const int t = 16 * seg + i; const float q = bf2f(R.q[i]);
;             const unsigned qh = pk2_rne(q * __expf(bt), q * __expf(bt - bmid));
;             const unsigned kk = pk2_rne((1.f - __expf(lf[i])) * __expf(bmid - bt), 0.f);
;             QH[t * 136 + k] = (bf16_t)(qh & 0xffffu); QT[t * 136 + k] = (bf16_t)(qh >> 16); KT2[t * 136 + k] = (bf16_t)(kk & 0xffffu);
;         }
; #pragma unroll
;         for (int i = 0; i < 8; ++i) pv[i] = (unsigned)R.vv[2 * i] | ((unsigned)R.vv[2 * i + 1] << 16);
;         *(LAS u32x4*)(VT + k * 72 + 16 * seg) = (u32x4){pv[0], pv[1], pv[2], pv[3]}; *(LAS u32x4*)(VT + k * 72 + 16 * seg + 8) = (u32x4){pv[4], pv[5], pv[6], pv[7]};
;     }
;     __syncthreads();
	v_cvt_pk_bf16_f32 v11, v11, s0
	ds_write_b16 v75, v8 offset:2720
	ds_write_b16_d16_hi v75, v8 offset:20128
	ds_write_b16 v75, v11 offset:37536
	v_add_f32_e32 v11, v184, v10
	v_mul_f32_e32 v115, 0x3fb8aa3b, v11
	v_exp_f32_e32 v150, v115
	v_sub_f32_e32 v115, v11, v9
	v_mul_f32_e32 v115, 0x3fb8aa3b, v115
	v_exp_f32_e32 v151, v115
	v_mul_f32_e32 v115, 0x3fb8aa3b, v183
	v_sub_f32_e32 v11, v9, v11
	v_exp_f32_e32 v115, v115
	v_mul_f32_e32 v11, 0x3fb8aa3b, v11
	v_exp_f32_e32 v11, v11
	v_lshlrev_b32_e32 v8, 16, v121
	v_sub_f32_e32 v115, 1.0, v115
	v_pk_mul_f32 v[150:151], v[150:151], v[8:9] op_sel_hi:[1,0]
	v_mul_f32_e32 v11, v115, v11
	v_cvt_pk_bf16_f32 v8, v150, v151
	v_cvt_pk_bf16_f32 v11, v11, s0
	ds_write_b16 v75, v8 offset:2992
	ds_write_b16_d16_hi v75, v8 offset:20400
	ds_write_b16 v75, v11 offset:37808
	v_add_f32_e32 v11, v186, v10
	v_lshlrev_b32_e32 v8, 16, v15
	v_mul_f32_e32 v15, 0x3fb8aa3b, v11
	v_exp_f32_e32 v150, v15
	v_sub_f32_e32 v15, v11, v9
	v_mul_f32_e32 v15, 0x3fb8aa3b, v15
	v_exp_f32_e32 v151, v15
	v_mul_f32_e32 v15, 0x3fb8aa3b, v185
	v_sub_f32_e32 v11, v9, v11
	v_exp_f32_e32 v15, v15
	v_mul_f32_e32 v11, 0x3fb8aa3b, v11
	v_exp_f32_e32 v11, v11
	v_pk_mul_f32 v[150:151], v[150:151], v[8:9] op_sel_hi:[1,0]
	v_sub_f32_e32 v15, 1.0, v15
	v_cvt_pk_bf16_f32 v8, v150, v151
	v_mul_f32_e32 v11, v15, v11
	v_cvt_pk_bf16_f32 v11, v11, s0
	ds_write_b16 v75, v8 offset:3264
	ds_write_b16_d16_hi v75, v8 offset:20672
	ds_write_b16 v75, v11 offset:38080
	v_add_f32_e32 v11, v188, v10
	v_sub_f32_e32 v15, v11, v9
	v_lshlrev_b32_e32 v8, 16, v14
	v_mul_f32_e32 v14, 0x3fb8aa3b, v11
	v_mul_f32_e32 v15, 0x3fb8aa3b, v15
	v_exp_f32_e32 v14, v14
	v_exp_f32_e32 v15, v15
	v_mul_f32_e32 v115, 0x3fb8aa3b, v187
	v_sub_f32_e32 v11, v9, v11
	v_exp_f32_e32 v115, v115
	v_mul_f32_e32 v11, 0x3fb8aa3b, v11
	v_exp_f32_e32 v11, v11
	v_pk_mul_f32 v[14:15], v[14:15], v[8:9] op_sel_hi:[1,0]
	v_mov_b32_e32 v119, v61
	v_cvt_pk_bf16_f32 v8, v14, v15
	v_sub_f32_e32 v14, 1.0, v115
	v_mul_f32_e32 v11, v14, v11
	v_cvt_pk_bf16_f32 v11, v11, s0
	ds_write_b16 v75, v8 offset:3536
	ds_write_b16_d16_hi v75, v8 offset:20944
	ds_write_b16 v75, v11 offset:38352
	v_add_f32_e32 v11, v190, v10
	v_lshlrev_b32_e32 v8, 16, v13
	v_mul_f32_e32 v13, 0x3fb8aa3b, v11
	v_exp_f32_e32 v14, v13
	v_sub_f32_e32 v13, v11, v9
	v_mul_f32_e32 v13, 0x3fb8aa3b, v13
	v_exp_f32_e32 v15, v13
	v_mul_f32_e32 v13, 0x3fb8aa3b, v189
	v_sub_f32_e32 v11, v9, v11
	v_exp_f32_e32 v13, v13
	v_mul_f32_e32 v11, 0x3fb8aa3b, v11
	v_exp_f32_e32 v11, v11
	v_pk_mul_f32 v[14:15], v[14:15], v[8:9] op_sel_hi:[1,0]
	v_sub_f32_e32 v13, 1.0, v13
	v_cvt_pk_bf16_f32 v8, v14, v15
	v_mul_f32_e32 v11, v13, v11
	v_cvt_pk_bf16_f32 v11, v11, s0
	v_add_f32_e32 v13, v193, v10
	ds_write_b16 v75, v8 offset:3808
	ds_write_b16_d16_hi v75, v8 offset:21216
	ds_write_b16 v75, v11 offset:38624
	v_sub_f32_e32 v11, v13, v9
	v_mul_f32_e32 v10, 0x3fb8aa3b, v13
	v_mul_f32_e32 v11, 0x3fb8aa3b, v11
	v_lshlrev_b32_e32 v8, 16, v12
	v_exp_f32_e32 v10, v10
	v_exp_f32_e32 v11, v11
	v_mul_f32_e32 v12, 0x3fb8aa3b, v192
	v_sub_f32_e32 v9, v9, v13
	v_exp_f32_e32 v12, v12
	v_mul_f32_e32 v9, 0x3fb8aa3b, v9
	v_exp_f32_e32 v13, v9
	v_pk_mul_f32 v[8:9], v[10:11], v[8:9] op_sel_hi:[1,0]
	v_mov_b32_e32 v115, v77
	v_cvt_pk_bf16_f32 v8, v8, v9
	v_sub_f32_e32 v9, 1.0, v12
	v_mul_f32_e32 v9, v9, v13
	v_cvt_pk_bf16_f32 v9, v9, s0
	ds_write_b16 v75, v8 offset:4080
	ds_write_b16_d16_hi v75, v8 offset:21488
	ds_write_b16 v75, v9 offset:38896
	ds_write_b128 v103, v[0:3] offset:52224
	ds_write_b128 v103, v[4:7] offset:52240
	s_waitcnt lgkmcnt(0)
	s_barrier
	s_cbranch_vccnz .LBB0_732
	s_andn2_b64 vcc, exec, s[26:27]
	s_cbranch_vccz .LBB0_730
	v_mov_b32_e32 v0, 0
	s_mov_b32 s2, 0
	v_mov_b32_e32 v119, v102
	v_mov_b32_e32 v115, v101
	v_mov_b32_e32 v121, v72
	v_mov_b32_e32 v1, 0
	v_mov_b32_e32 v2, 0
	v_mov_b32_e32 v3, 0
	v_mov_b32_e32 v4, 0
	v_mov_b32_e32 v5, 0
	v_mov_b32_e32 v6, 0
	v_mov_b32_e32 v7, 0
	v_mov_b32_e32 v8, 0
	v_mov_b32_e32 v9, 0
	v_mov_b32_e32 v10, 0
	v_mov_b32_e32 v11, 0
	v_mov_b32_e32 v12, 0
	v_mov_b32_e32 v13, 0
	v_mov_b32_e32 v14, 0
	v_mov_b32_e32 v15, 0
	s_branch .LBB0_731
